# conv own-tile loads: counted waits instead of two full drains (on top of the GEMV load batching)
# speedup vs baseline: 1.0205x; 1.0036x over previous
; __device__ __forceinline__ float bf_lo(unsigned w) { return __uint_as_float(w << 16); }
; __device__ __forceinline__ float bf_hi(unsigned w) { return __uint_as_float(w & 0xffff0000u); }
; __device__ __forceinline__ void conv_own_tiles(const bf16_t* XB, const float* cw, const float* cb, bf16_t* XC) {
;     ...
;         for (int k = 0; k < 19; ++k) xr[k] = (rb == 0 && k < 3) ? (u32x4){0u, 0u, 0u, 0u} : *(const u32x4*)(XB + (row0 + k - 3) * DM + ch);
; #pragma unroll
;         for (int r = 0; r < 16; ++r) {
;             if (rb == 0 && r < 3) continue;
;             f32x4 a0 = b0, a1 = b1;
; #pragma unroll
;             for (int wv = 0; wv < 4; ++wv) { const u32x4 x = xr[r + wv];
;                 a0 += w0[wv] * (f32x4){bf_lo(x.x), bf_hi(x.x), bf_lo(x.y), bf_hi(x.y)}; a1 += w1[wv] * (f32x4){bf_lo(x.z), bf_hi(x.z), bf_lo(x.w), bf_hi(x.w)}; }
.LBB0_853:
	s_or_b64 exec, exec, s[4:5]
	v_lshl_add_u64 v[42:43], s[88:89], 0, v[110:111]
	v_lshlrev_b64 v[120:121], 1, v[40:41]
	v_lshl_add_u64 v[40:41], v[42:43], 0, v[120:121]
	s_movk_i32 s4, 0x2000
	v_add_co_u32_e32 v42, vcc, s4, v40
	global_load_dwordx4 v[112:115], v[40:41], off
	s_nop 0
	v_addc_co_u32_e32 v43, vcc, 0, v41, vcc
	global_load_dwordx4 v[116:119], v[42:43], off offset:-4096
	global_load_dwordx4 v[138:141], v[42:43], off
	v_add_co_u32_e32 v42, vcc, s33, v40
	v_lshl_add_u64 v[120:121], s[6:7], 0, v[120:121]
	s_nop 0
	v_addc_co_u32_e32 v43, vcc, 0, v41, vcc
	global_load_dwordx4 v[88:91], v[42:43], off offset:-4096
	global_load_dwordx4 v[84:87], v[42:43], off
	v_add_co_u32_e32 v42, vcc, s50, v40
	v_lshl_add_u64 v[110:111], v[120:121], 0, v[110:111]
	s_nop 0
	v_addc_co_u32_e32 v43, vcc, 0, v41, vcc
	global_load_dwordx4 v[80:83], v[42:43], off offset:-4096
	global_load_dwordx4 v[76:79], v[42:43], off
	v_add_co_u32_e32 v42, vcc, s52, v40
	s_waitcnt vmcnt(6)
	v_lshlrev_b32_e32 v132, 16, v112
	v_addc_co_u32_e32 v43, vcc, 0, v41, vcc
	global_load_dwordx4 v[72:75], v[42:43], off offset:-4096
	global_load_dwordx4 v[68:71], v[42:43], off
	v_add_co_u32_e32 v42, vcc, s53, v40
	v_and_b32_e32 v133, 0xffff0000, v112
	s_nop 0
	v_addc_co_u32_e32 v43, vcc, 0, v41, vcc
	global_load_dwordx4 v[64:67], v[42:43], off offset:-4096
	global_load_dwordx4 v[60:63], v[42:43], off
	v_add_co_u32_e32 v42, vcc, s54, v40
	v_lshlrev_b32_e32 v134, 16, v113
	s_nop 0
	v_addc_co_u32_e32 v43, vcc, 0, v41, vcc
	global_load_dwordx4 v[56:59], v[42:43], off offset:-4096
	global_load_dwordx4 v[52:55], v[42:43], off
	v_add_co_u32_e32 v42, vcc, s55, v40
	v_and_b32_e32 v135, 0xffff0000, v113
	s_nop 0
	v_addc_co_u32_e32 v43, vcc, 0, v41, vcc
	global_load_dwordx4 v[48:51], v[42:43], off
	v_add_co_u32_e32 v42, vcc, 0xe000, v40
	v_lshlrev_b32_e32 v128, 16, v114
	s_nop 0
	v_addc_co_u32_e32 v43, vcc, 0, v41, vcc
	v_add_co_u32_e32 v40, vcc, 0xf000, v40
	v_and_b32_e32 v129, 0xffff0000, v114
	s_nop 0
	v_addc_co_u32_e32 v41, vcc, 0, v41, vcc
	global_load_dwordx4 v[44:47], v[42:43], off
	s_nop 0
	global_load_dwordx4 v[40:43], v[40:41], off
	s_waitcnt vmcnt(9)
	v_lshlrev_b32_e32 v130, 16, v115
	v_and_b32_e32 v131, 0xffff0000, v115
	v_lshlrev_b32_e32 v120, 16, v116
	v_and_b32_e32 v121, 0xffff0000, v116
	v_lshlrev_b32_e32 v124, 16, v117
	v_and_b32_e32 v125, 0xffff0000, v117
	v_lshlrev_b32_e32 v122, 16, v118
	v_and_b32_e32 v123, 0xffff0000, v118
	v_lshlrev_b32_e32 v126, 16, v119
	v_and_b32_e32 v127, 0xffff0000, v119
	v_lshlrev_b32_e32 v112, 16, v138
	v_and_b32_e32 v113, 0xffff0000, v138
	v_lshlrev_b32_e32 v116, 16, v139
	v_and_b32_e32 v117, 0xffff0000, v139
	v_lshlrev_b32_e32 v114, 16, v140
	v_and_b32_e32 v115, 0xffff0000, v140
	v_lshlrev_b32_e32 v118, 16, v141
	v_and_b32_e32 v119, 0xffff0000, v141
	s_and_saveexec_b64 s[4:5], s[0:1]
	s_xor_b64 s[4:5], exec, s[4:5]
	s_cbranch_execz .LBB0_855
; __device__ __forceinline__ unsigned cvt_pk_bf16(float lo, float hi) { const bf16x2_t r = __builtin_convertvector((f32x2){lo, hi}, bf16x2_t); return __builtin_bit_cast(unsigned, r); }
; __device__ __forceinline__ float bf_lo(unsigned w) { return __uint_as_float(w << 16); }
; __device__ __forceinline__ float bf_hi(unsigned w) { return __uint_as_float(w & 0xffff0000u); }
; __device__ __forceinline__ void conv_own_tiles(const bf16_t* XB, const float* cw, const float* cb, bf16_t* XC) {
;     ...
;         for (int r = 0; r < 16; ++r) {
;             if (rb == 0 && r < 3) continue;
;             f32x4 a0 = b0, a1 = b1;
; #pragma unroll
;             for (int wv = 0; wv < 4; ++wv) { const u32x4 x = xr[r + wv];
;                 a0 += w0[wv] * (f32x4){bf_lo(x.x), bf_hi(x.x), bf_lo(x.y), bf_hi(x.y)}; a1 += w1[wv] * (f32x4){bf_lo(x.z), bf_hi(x.z), bf_lo(x.w), bf_hi(x.w)}; }
;             u32x4 o; o.x = cvt_pk_bf16(a0[0], a0[1]); o.y = cvt_pk_bf16(a0[2], a0[3]); o.z = cvt_pk_bf16(a1[0], a1[1]); o.w = cvt_pk_bf16(a1[2], a1[3]);
;             *(u32x4*)(XC + (row0 + r) * DM + ch) = o; }
	v_lshlrev_b32_e32 v138, 16, v96
	v_and_b32_e32 v139, 0xffff0000, v96
	v_lshlrev_b32_e32 v96, 16, v97
	v_and_b32_e32 v97, 0xffff0000, v97
	v_pk_fma_f32 v[138:139], v[8:9], v[138:139], v[36:37]
	v_pk_fma_f32 v[96:97], v[10:11], v[96:97], v[38:39]
	v_lshlrev_b32_e32 v140, 16, v98
	v_and_b32_e32 v141, 0xffff0000, v98
	v_lshlrev_b32_e32 v98, 16, v99
	v_and_b32_e32 v99, 0xffff0000, v99
	v_lshlrev_b32_e32 v142, 16, v92
	v_and_b32_e32 v143, 0xffff0000, v92
	v_lshlrev_b32_e32 v144, 16, v93
	v_and_b32_e32 v145, 0xffff0000, v93
	v_pk_fma_f32 v[140:141], v[4:5], v[140:141], v[32:33]
	v_pk_fma_f32 v[98:99], v[6:7], v[98:99], v[34:35]
	v_pk_fma_f32 v[92:93], v[18:19], v[144:145], v[96:97]
	v_pk_fma_f32 v[96:97], v[16:17], v[142:143], v[138:139]
	v_lshlrev_b32_e32 v138, 16, v94
	v_and_b32_e32 v139, 0xffff0000, v94
	v_lshlrev_b32_e32 v146, 16, v95
	v_and_b32_e32 v147, 0xffff0000, v95
	v_pk_fma_f32 v[94:95], v[14:15], v[146:147], v[98:99]
	v_pk_fma_f32 v[98:99], v[12:13], v[138:139], v[140:141]
	v_lshlrev_b32_e32 v140, 16, v100
	v_and_b32_e32 v141, 0xffff0000, v100
	v_lshlrev_b32_e32 v100, 16, v101
	v_and_b32_e32 v101, 0xffff0000, v101
	v_lshlrev_b32_e32 v148, 16, v102
	v_and_b32_e32 v149, 0xffff0000, v102
	v_lshlrev_b32_e32 v102, 16, v103
	v_and_b32_e32 v103, 0xffff0000, v103
	v_pk_fma_f32 v[96:97], v[28:29], v[140:141], v[96:97]
	v_pk_fma_f32 v[92:93], v[30:31], v[100:101], v[92:93]
	v_pk_fma_f32 v[98:99], v[24:25], v[148:149], v[98:99]
	v_pk_fma_f32 v[94:95], v[26:27], v[102:103], v[94:95]
	v_pk_fma_f32 v[150:151], v[22:23], v[134:135], v[92:93]
	v_pk_fma_f32 v[92:93], v[20:21], v[132:133], v[96:97]
	v_pk_fma_f32 v[96:97], v[2:3], v[130:131], v[94:95]
	v_pk_fma_f32 v[94:95], v[0:1], v[128:129], v[98:99]
	v_cvt_pk_bf16_f32 v92, v92, v93
	v_cvt_pk_bf16_f32 v93, v150, v151
	v_cvt_pk_bf16_f32 v94, v94, v95
	v_cvt_pk_bf16_f32 v95, v96, v97
	global_store_dwordx4 v[110:111], v[92:95], off
	v_pk_fma_f32 v[96:97], v[4:5], v[138:139], v[32:33]
	v_pk_fma_f32 v[98:99], v[6:7], v[146:147], v[34:35]
	v_pk_fma_f32 v[92:93], v[8:9], v[142:143], v[36:37]
	v_pk_fma_f32 v[94:95], v[10:11], v[144:145], v[38:39]
	v_pk_fma_f32 v[92:93], v[16:17], v[140:141], v[92:93]
	v_pk_fma_f32 v[94:95], v[18:19], v[100:101], v[94:95]
	v_pk_fma_f32 v[96:97], v[12:13], v[148:149], v[96:97]
	v_pk_fma_f32 v[98:99], v[14:15], v[102:103], v[98:99]
	v_pk_fma_f32 v[92:93], v[28:29], v[132:133], v[92:93]
	v_pk_fma_f32 v[94:95], v[30:31], v[134:135], v[94:95]
	v_pk_fma_f32 v[96:97], v[24:25], v[128:129], v[96:97]
	v_pk_fma_f32 v[98:99], v[26:27], v[130:131], v[98:99]
	v_pk_fma_f32 v[94:95], v[22:23], v[124:125], v[94:95]
	v_pk_fma_f32 v[92:93], v[20:21], v[120:121], v[92:93]
	v_pk_fma_f32 v[96:97], v[0:1], v[122:123], v[96:97]
	v_pk_fma_f32 v[98:99], v[2:3], v[126:127], v[98:99]
	v_cvt_pk_bf16_f32 v92, v92, v93
	v_cvt_pk_bf16_f32 v93, v94, v95
	v_cvt_pk_bf16_f32 v94, v96, v97
	v_add_co_u32_e32 v96, vcc, s51, v110
	v_cvt_pk_bf16_f32 v95, v98, v99
	s_nop 0
	v_addc_co_u32_e32 v97, vcc, 0, v111, vcc
	global_store_dwordx4 v[96:97], v[92:95], off
	v_pk_fma_f32 v[96:97], v[4:5], v[148:149], v[32:33]
	v_pk_fma_f32 v[98:99], v[6:7], v[102:103], v[34:35]
	v_pk_fma_f32 v[92:93], v[8:9], v[140:141], v[36:37]
	v_pk_fma_f32 v[94:95], v[10:11], v[100:101], v[38:39]
	v_pk_fma_f32 v[92:93], v[16:17], v[132:133], v[92:93]
	v_pk_fma_f32 v[94:95], v[18:19], v[134:135], v[94:95]
	v_pk_fma_f32 v[96:97], v[12:13], v[128:129], v[96:97]
	v_pk_fma_f32 v[98:99], v[14:15], v[130:131], v[98:99]
	v_pk_fma_f32 v[92:93], v[28:29], v[120:121], v[92:93]
	v_pk_fma_f32 v[94:95], v[30:31], v[124:125], v[94:95]
	v_pk_fma_f32 v[96:97], v[24:25], v[122:123], v[96:97]
	v_pk_fma_f32 v[98:99], v[26:27], v[126:127], v[98:99]
	v_pk_fma_f32 v[94:95], v[22:23], v[116:117], v[94:95]
	v_pk_fma_f32 v[92:93], v[20:21], v[112:113], v[92:93]
	v_pk_fma_f32 v[96:97], v[0:1], v[114:115], v[96:97]
	v_pk_fma_f32 v[98:99], v[2:3], v[118:119], v[98:99]
	v_cvt_pk_bf16_f32 v92, v92, v93
	v_cvt_pk_bf16_f32 v93, v94, v95
	v_cvt_pk_bf16_f32 v94, v96, v97
	v_add_co_u32_e32 v96, vcc, 0x2000, v110
	v_cvt_pk_bf16_f32 v95, v98, v99
	s_nop 0
	v_addc_co_u32_e32 v97, vcc, 0, v111, vcc
	global_store_dwordx4 v[96:97], v[92:95], off
